# pass_b: at most 60 VMEM ops outstanding (6-bit vmcnt), scan16 hand-scheduled scanner, RG-LRU pass-2 gate loads batched
# speedup vs baseline: 1.0496x; 1.0084x over previous
.Lpb_zpdone:
	s_waitcnt vmcnt(12)
	global_load_dword v130, v[88:89], off
	global_load_dword v131, v[90:91], off
	global_load_dword v132, v[92:93], off
	global_load_dword v133, v[94:95], off
	global_load_dword v134, v[96:97], off
	global_load_dword v135, v[98:99], off
	global_load_dword v140, v[110:111], off
	global_load_dword v141, v[112:113], off
	global_load_dword v136, v[100:101], off
	global_load_dword v137, v[102:103], off
	global_load_dword v138, v[106:107], off
	global_load_dword v139, v[108:109], off
	global_load_dword v142, v[114:115], off
	global_load_dword v143, v[116:117], off
	global_load_dword v144, v[118:119], off
	global_load_dword v145, v[120:121], off
	global_load_dword v146, v[88:89], off offset:256
	global_load_dword v147, v[90:91], off offset:256
	global_load_dword v148, v[92:93], off offset:256
	global_load_dword v149, v[94:95], off offset:256
	global_load_dword v150, v[96:97], off offset:256
	global_load_dword v151, v[98:99], off offset:256
	global_load_dword v156, v[110:111], off offset:256
	global_load_dword v157, v[112:113], off offset:256
	global_load_dword v152, v[100:101], off offset:256
	global_load_dword v153, v[102:103], off offset:256
	global_load_dword v154, v[106:107], off offset:256
	global_load_dword v155, v[108:109], off offset:256
	global_load_dword v158, v[114:115], off offset:256
	global_load_dword v159, v[116:117], off offset:256
	global_load_dword v160, v[118:119], off offset:256
	global_load_dword v161, v[120:121], off offset:256
	global_load_dword v174, v[88:89], off offset:512
	global_load_dword v175, v[90:91], off offset:512
	global_load_dword v176, v[92:93], off offset:512
	global_load_dword v177, v[94:95], off offset:512
	global_load_dword v178, v[96:97], off offset:512
	global_load_dword v179, v[98:99], off offset:512
	global_load_dword v184, v[110:111], off offset:512
	global_load_dword v185, v[112:113], off offset:512
	global_load_dword v180, v[100:101], off offset:512
	global_load_dword v181, v[102:103], off offset:512
	global_load_dword v182, v[106:107], off offset:512
	global_load_dword v183, v[108:109], off offset:512
	global_load_dword v186, v[114:115], off offset:512
	global_load_dword v187, v[116:117], off offset:512
	global_load_dword v188, v[118:119], off offset:512
	global_load_dword v189, v[120:121], off offset:512
	s_waitcnt vmcnt(32)
	global_load_dword v217, v[88:89], off offset:768
	global_load_dword v218, v[90:91], off offset:768
	global_load_dword v219, v[92:93], off offset:768
	global_load_dword v220, v[94:95], off offset:768
	global_load_dword v221, v[96:97], off offset:768
	global_load_dword v222, v[98:99], off offset:768
	global_load_dword v227, v[110:111], off offset:768
	global_load_dword v228, v[112:113], off offset:768
	global_load_dword v223, v[100:101], off offset:768
	global_load_dword v224, v[102:103], off offset:768
	global_load_dword v225, v[106:107], off offset:768
	global_load_dword v226, v[108:109], off offset:768
	global_load_dword v229, v[114:115], off offset:768
	global_load_dword v230, v[116:117], off offset:768
	global_load_dword v231, v[118:119], off offset:768
	global_load_dword v232, v[120:121], off offset:768
	v_cndmask_b32_e64 v133, 0, v133, s[24:25]
	v_cndmask_b32_e64 v134, 0, v134, s[24:25]
	v_cndmask_b32_e64 v135, 0, v135, s[24:25]
	v_sub_f32_e32 v133, v133, v130
	v_sub_f32_e32 v134, v134, v131
	v_fmac_f32_e32 v130, v133, v136
	v_fmac_f32_e32 v131, v134, v137
	v_add_f32_e32 v54, v142, v141
	v_mul_f32_e32 v54, 0xbfb8aa3b, v54
	v_exp_f32_e32 v54, v54
	v_mul_f32_e32 v56, v131, v143
	v_mul_f32_e32 v59, v56, v56
	v_add_f32_e32 v54, 1.0, v54
	v_rcp_f32_e32 v54, v54
	v_mov_b32_dpp v59, v59 quad_perm:[1,0,3,2] row_mask:0xf bank_mask:0xf bound_ctrl:1
	v_fmac_f32_e32 v59, v56, v56
	s_nop 1
	v_add_f32_dpp v59, v59, v59 quad_perm:[2,3,0,1] row_mask:0xf bank_mask:0xf bound_ctrl:1
	s_nop 1
	v_add_f32_dpp v59, v59, v59 row_half_mirror row_mask:0xf bank_mask:0xf bound_ctrl:1
	s_nop 1
	v_add_f32_dpp v59, v59, v59 row_mirror row_mask:0xf bank_mask:0xf bound_ctrl:1
	s_nop 0
	v_readlane_b32 s4, v59, 0
	v_readlane_b32 s5, v59, 16
	v_readlane_b32 s2, v59, 32
	v_readlane_b32 s3, v59, 48
	v_add_f32_e32 v59, -1.0, v54
	v_fma_f32 v59, v59, v144, 1.0
	v_mul_f32_e32 v131, v131, v59
	v_mul_f32_e32 v59, v130, v131
	v_mul_f32_e32 v61, v145, v59
	s_nop 1
	v_mov_b32_dpp v61, v61 quad_perm:[1,0,3,2] row_mask:0xf bank_mask:0xf bound_ctrl:1
	v_fmac_f32_e32 v61, v145, v59
	s_nop 1
	v_add_f32_dpp v59, v61, v61 quad_perm:[2,3,0,1] row_mask:0xf bank_mask:0xf bound_ctrl:1
	s_nop 1
	v_add_f32_dpp v59, v59, v59 row_half_mirror row_mask:0xf bank_mask:0xf bound_ctrl:1
	s_nop 1
	v_add_f32_dpp v59, v59, v59 row_mirror row_mask:0xf bank_mask:0xf bound_ctrl:1
	s_nop 0
	v_readlane_b32 s18, v59, 0
	v_readlane_b32 s33, v59, 16
	v_readlane_b32 s19, v59, 32
	v_readlane_b32 s46, v59, 48
	s_and_b64 vcc, exec, s[12:13]
	s_cbranch_vccz .Lpb_smp0
	s_add_i32 s10, s44, s45
	s_ashr_i32 s11, s10, 31
	s_lshl_b64 s[10:11], s[10:11], 11
	s_or_b32 s10, s10, s43
	s_mulk_i32 s11, 0x180
	s_mul_hi_u32 s34, s10, 0x180
	s_add_i32 s35, s34, s11
	s_mul_i32 s34, s10, 0x180
	s_branch .Lpb_adr0

.LBB0_1632:
	s_andn2_b64 vcc, exec, s[34:35]
	s_movk_i32 s2, 0x700
	s_cbranch_vccnz .LBB0_1634
	s_movk_i32 s2, 0xf00
	v_add_f32_dpp v234, v63, v63 quad_perm:[1,0,3,2] row_mask:0xf bank_mask:0xf bound_ctrl:1
	v_mov_b32_e32 v240, v53
	s_nop 0
	v_add_f32_dpp v234, v234, v234 quad_perm:[2,3,0,1] row_mask:0xf bank_mask:0xf bound_ctrl:1
	s_nop 1
	v_add_f32_dpp v234, v234, v234 row_half_mirror row_mask:0xf bank_mask:0xf bound_ctrl:1
	s_nop 1
	v_add_f32_dpp v234, v234, v234 row_mirror row_mask:0xf bank_mask:0xf bound_ctrl:1
	v_pk_fma_f32 v[36:37], v[32:33], v[234:235], v[54:55] op_sel_hi:[1,0,1]
	v_pk_fma_f32 v[34:35], v[30:31], v[234:235], v[56:57] op_sel_hi:[1,0,1]
	ds_read_b128 v[224:227], v51 offset:3840
	s_waitcnt lgkmcnt(7)
	v_pk_mul_f32 v[232:233], v[28:29], v[36:37]
	v_pk_fma_f32 v[232:233], v[26:27], v[34:35], v[232:233]
	ds_read_b128 v[64:67], v51 offset:3328
	ds_read_b128 v[68:71], v51 offset:3584
	v_add_f32_e32 v234, v232, v233
	v_pk_mul_f32 v[236:237], v[24:25], v[36:37]
	v_pk_fma_f32 v[236:237], v[22:23], v[34:35], v[236:237]
	v_add_f32_dpp v234, v234, v234 quad_perm:[1,0,3,2] row_mask:0xf bank_mask:0xf bound_ctrl:1
	s_waitcnt lgkmcnt(6)
	v_pk_mul_f32 v[228:229], v[18:19], v[34:35]
	v_add_f32_e32 v238, v236, v237
	v_add_f32_dpp v234, v234, v234 quad_perm:[2,3,0,1] row_mask:0xf bank_mask:0xf bound_ctrl:1
	v_pk_mul_f32 v[230:231], v[20:21], v[36:37]
	v_pk_fma_f32 v[56:57], v[14:15], v[240:241], v[228:229] op_sel_hi:[1,0,1]
	v_add_f32_dpp v234, v234, v234 row_half_mirror row_mask:0xf bank_mask:0xf bound_ctrl:1
	v_pk_fma_f32 v[54:55], v[16:17], v[240:241], v[230:231] op_sel_hi:[1,0,1]
	v_add_f32_dpp v238, v238, v238 quad_perm:[1,0,3,2] row_mask:0xf bank_mask:0xf bound_ctrl:1
	v_add_f32_dpp v234, v234, v234 row_mirror row_mask:0xf bank_mask:0xf bound_ctrl:1
	ds_read_b32 v242, v62 offset:4352
	ds_read_b128 v[30:33], v51 offset:4096
	ds_read_b128 v[22:25], v51 offset:3072
	s_waitcnt lgkmcnt(8)
	v_pk_fma_f32 v[36:37], v[12:13], v[234:235], v[54:55] op_sel_hi:[1,0,1]
	v_pk_fma_f32 v[34:35], v[10:11], v[234:235], v[56:57] op_sel_hi:[1,0,1]
	v_add_f32_dpp v238, v238, v238 quad_perm:[2,3,0,1] row_mask:0xf bank_mask:0xf bound_ctrl:1
	ds_write_b32 v49, v238
	ds_read_b128 v[26:29], v51 offset:5376
	s_waitcnt lgkmcnt(7)
	v_pk_mul_f32 v[232:233], v[226:227], v[36:37]
	v_pk_fma_f32 v[232:233], v[224:225], v[34:35], v[232:233]
	ds_read_b128 v[18:21], v51 offset:4864
	ds_read_b128 v[14:17], v51 offset:5120
	v_add_f32_e32 v234, v232, v233
	v_pk_mul_f32 v[236:237], v[8:9], v[36:37]
	v_pk_fma_f32 v[236:237], v[6:7], v[34:35], v[236:237]
	v_add_f32_dpp v234, v234, v234 quad_perm:[1,0,3,2] row_mask:0xf bank_mask:0xf bound_ctrl:1
	s_waitcnt lgkmcnt(6)
	v_pk_mul_f32 v[228:229], v[64:65], v[34:35]
	v_add_f32_e32 v238, v236, v237
	v_add_f32_dpp v234, v234, v234 quad_perm:[2,3,0,1] row_mask:0xf bank_mask:0xf bound_ctrl:1
	v_pk_mul_f32 v[230:231], v[66:67], v[36:37]
	v_pk_fma_f32 v[56:57], v[68:69], v[242:243], v[228:229] op_sel_hi:[1,0,1]
	v_add_f32_dpp v234, v234, v234 row_half_mirror row_mask:0xf bank_mask:0xf bound_ctrl:1
	v_pk_fma_f32 v[54:55], v[70:71], v[242:243], v[230:231] op_sel_hi:[1,0,1]
	v_add_f32_dpp v238, v238, v238 quad_perm:[1,0,3,2] row_mask:0xf bank_mask:0xf bound_ctrl:1
	v_add_f32_dpp v234, v234, v234 row_mirror row_mask:0xf bank_mask:0xf bound_ctrl:1
	ds_read_b32 v240, v62 offset:5888
	ds_read_b128 v[10:13], v51 offset:5632
	ds_read_b128 v[6:9], v51 offset:4608
	s_waitcnt lgkmcnt(8)
	v_pk_fma_f32 v[36:37], v[32:33], v[234:235], v[54:55] op_sel_hi:[1,0,1]
	v_pk_fma_f32 v[34:35], v[30:31], v[234:235], v[56:57] op_sel_hi:[1,0,1]
	v_add_f32_dpp v238, v238, v238 quad_perm:[2,3,0,1] row_mask:0xf bank_mask:0xf bound_ctrl:1
	ds_write_b32 v49, v238 offset:256
	ds_read_b128 v[224:227], v51 offset:6912
	s_waitcnt lgkmcnt(7)
	v_pk_mul_f32 v[232:233], v[28:29], v[36:37]
	v_pk_fma_f32 v[232:233], v[26:27], v[34:35], v[232:233]
	ds_read_b128 v[64:67], v51 offset:6400
	ds_read_b128 v[68:71], v51 offset:6656
	v_add_f32_e32 v234, v232, v233
	v_pk_mul_f32 v[236:237], v[24:25], v[36:37]
	v_pk_fma_f32 v[236:237], v[22:23], v[34:35], v[236:237]
	v_add_f32_dpp v234, v234, v234 quad_perm:[1,0,3,2] row_mask:0xf bank_mask:0xf bound_ctrl:1
	s_waitcnt lgkmcnt(6)
	v_pk_mul_f32 v[228:229], v[18:19], v[34:35]
	v_add_f32_e32 v238, v236, v237
	v_add_f32_dpp v234, v234, v234 quad_perm:[2,3,0,1] row_mask:0xf bank_mask:0xf bound_ctrl:1
	v_pk_mul_f32 v[230:231], v[20:21], v[36:37]
	v_pk_fma_f32 v[56:57], v[14:15], v[240:241], v[228:229] op_sel_hi:[1,0,1]
	v_add_f32_dpp v234, v234, v234 row_half_mirror row_mask:0xf bank_mask:0xf bound_ctrl:1
	v_pk_fma_f32 v[54:55], v[16:17], v[240:241], v[230:231] op_sel_hi:[1,0,1]
	v_add_f32_dpp v238, v238, v238 quad_perm:[1,0,3,2] row_mask:0xf bank_mask:0xf bound_ctrl:1
	v_add_f32_dpp v234, v234, v234 row_mirror row_mask:0xf bank_mask:0xf bound_ctrl:1
	ds_read_b32 v242, v62 offset:7424
	ds_read_b128 v[30:33], v51 offset:7168
	ds_read_b128 v[22:25], v51 offset:6144
	s_waitcnt lgkmcnt(8)
	v_pk_fma_f32 v[36:37], v[12:13], v[234:235], v[54:55] op_sel_hi:[1,0,1]
	v_pk_fma_f32 v[34:35], v[10:11], v[234:235], v[56:57] op_sel_hi:[1,0,1]
	v_add_f32_dpp v238, v238, v238 quad_perm:[2,3,0,1] row_mask:0xf bank_mask:0xf bound_ctrl:1
	ds_write_b32 v49, v238 offset:512
	ds_read_b128 v[26:29], v51 offset:8448
	s_waitcnt lgkmcnt(7)
	v_pk_mul_f32 v[232:233], v[226:227], v[36:37]
	v_pk_fma_f32 v[232:233], v[224:225], v[34:35], v[232:233]
	ds_read_b128 v[18:21], v51 offset:7936
	ds_read_b128 v[14:17], v51 offset:8192
	v_add_f32_e32 v234, v232, v233
	v_pk_mul_f32 v[236:237], v[8:9], v[36:37]
	v_pk_fma_f32 v[236:237], v[6:7], v[34:35], v[236:237]
	v_add_f32_dpp v234, v234, v234 quad_perm:[1,0,3,2] row_mask:0xf bank_mask:0xf bound_ctrl:1
	s_waitcnt lgkmcnt(6)
	v_pk_mul_f32 v[228:229], v[64:65], v[34:35]
	v_add_f32_e32 v238, v236, v237
	v_add_f32_dpp v234, v234, v234 quad_perm:[2,3,0,1] row_mask:0xf bank_mask:0xf bound_ctrl:1
	v_pk_mul_f32 v[230:231], v[66:67], v[36:37]
	v_pk_fma_f32 v[56:57], v[68:69], v[242:243], v[228:229] op_sel_hi:[1,0,1]
	v_add_f32_dpp v234, v234, v234 row_half_mirror row_mask:0xf bank_mask:0xf bound_ctrl:1
	v_pk_fma_f32 v[54:55], v[70:71], v[242:243], v[230:231] op_sel_hi:[1,0,1]
	v_add_f32_dpp v238, v238, v238 quad_perm:[1,0,3,2] row_mask:0xf bank_mask:0xf bound_ctrl:1
	v_add_f32_dpp v234, v234, v234 row_mirror row_mask:0xf bank_mask:0xf bound_ctrl:1
	ds_read_b32 v240, v62 offset:8960
	ds_read_b128 v[10:13], v51 offset:8704
	ds_read_b128 v[6:9], v51 offset:7680
	s_waitcnt lgkmcnt(8)
	v_pk_fma_f32 v[36:37], v[32:33], v[234:235], v[54:55] op_sel_hi:[1,0,1]
	v_pk_fma_f32 v[34:35], v[30:31], v[234:235], v[56:57] op_sel_hi:[1,0,1]
	v_add_f32_dpp v238, v238, v238 quad_perm:[2,3,0,1] row_mask:0xf bank_mask:0xf bound_ctrl:1
	ds_write_b32 v49, v238 offset:768
	ds_read_b128 v[224:227], v51 offset:9984
	s_waitcnt lgkmcnt(7)
	v_pk_mul_f32 v[232:233], v[28:29], v[36:37]
	v_pk_fma_f32 v[232:233], v[26:27], v[34:35], v[232:233]
	ds_read_b128 v[64:67], v51 offset:9472
	ds_read_b128 v[68:71], v51 offset:9728
	v_add_f32_e32 v234, v232, v233
	v_pk_mul_f32 v[236:237], v[24:25], v[36:37]
	v_pk_fma_f32 v[236:237], v[22:23], v[34:35], v[236:237]
	v_add_f32_dpp v234, v234, v234 quad_perm:[1,0,3,2] row_mask:0xf bank_mask:0xf bound_ctrl:1
	s_waitcnt lgkmcnt(6)
	v_pk_mul_f32 v[228:229], v[18:19], v[34:35]
	v_add_f32_e32 v238, v236, v237
	v_add_f32_dpp v234, v234, v234 quad_perm:[2,3,0,1] row_mask:0xf bank_mask:0xf bound_ctrl:1
	v_pk_mul_f32 v[230:231], v[20:21], v[36:37]
	v_pk_fma_f32 v[56:57], v[14:15], v[240:241], v[228:229] op_sel_hi:[1,0,1]
	v_add_f32_dpp v234, v234, v234 row_half_mirror row_mask:0xf bank_mask:0xf bound_ctrl:1
	v_pk_fma_f32 v[54:55], v[16:17], v[240:241], v[230:231] op_sel_hi:[1,0,1]
	v_add_f32_dpp v238, v238, v238 quad_perm:[1,0,3,2] row_mask:0xf bank_mask:0xf bound_ctrl:1
	v_add_f32_dpp v234, v234, v234 row_mirror row_mask:0xf bank_mask:0xf bound_ctrl:1
	ds_read_b32 v242, v62 offset:10496
	ds_read_b128 v[30:33], v51 offset:10240
	ds_read_b128 v[22:25], v51 offset:9216
	s_waitcnt lgkmcnt(8)
	v_pk_fma_f32 v[36:37], v[12:13], v[234:235], v[54:55] op_sel_hi:[1,0,1]
	v_pk_fma_f32 v[34:35], v[10:11], v[234:235], v[56:57] op_sel_hi:[1,0,1]
	v_add_f32_dpp v238, v238, v238 quad_perm:[2,3,0,1] row_mask:0xf bank_mask:0xf bound_ctrl:1
	ds_write_b32 v49, v238 offset:1024
	ds_read_b128 v[26:29], v51 offset:11520
	s_waitcnt lgkmcnt(7)
	v_pk_mul_f32 v[232:233], v[226:227], v[36:37]
	v_pk_fma_f32 v[232:233], v[224:225], v[34:35], v[232:233]
	ds_read_b128 v[18:21], v51 offset:11008
	ds_read_b128 v[14:17], v51 offset:11264
	v_add_f32_e32 v234, v232, v233
	v_pk_mul_f32 v[236:237], v[8:9], v[36:37]
	v_pk_fma_f32 v[236:237], v[6:7], v[34:35], v[236:237]
	v_add_f32_dpp v234, v234, v234 quad_perm:[1,0,3,2] row_mask:0xf bank_mask:0xf bound_ctrl:1
	s_waitcnt lgkmcnt(6)
	v_pk_mul_f32 v[228:229], v[64:65], v[34:35]
	v_add_f32_e32 v238, v236, v237
	v_add_f32_dpp v234, v234, v234 quad_perm:[2,3,0,1] row_mask:0xf bank_mask:0xf bound_ctrl:1
	v_pk_mul_f32 v[230:231], v[66:67], v[36:37]
	v_pk_fma_f32 v[56:57], v[68:69], v[242:243], v[228:229] op_sel_hi:[1,0,1]
	v_add_f32_dpp v234, v234, v234 row_half_mirror row_mask:0xf bank_mask:0xf bound_ctrl:1
	v_pk_fma_f32 v[54:55], v[70:71], v[242:243], v[230:231] op_sel_hi:[1,0,1]
	v_add_f32_dpp v238, v238, v238 quad_perm:[1,0,3,2] row_mask:0xf bank_mask:0xf bound_ctrl:1
	v_add_f32_dpp v234, v234, v234 row_mirror row_mask:0xf bank_mask:0xf bound_ctrl:1
	ds_read_b32 v240, v62 offset:12032
	ds_read_b128 v[10:13], v51 offset:11776
	ds_read_b128 v[6:9], v51 offset:10752
	s_waitcnt lgkmcnt(8)
	v_pk_fma_f32 v[36:37], v[32:33], v[234:235], v[54:55] op_sel_hi:[1,0,1]
	v_pk_fma_f32 v[34:35], v[30:31], v[234:235], v[56:57] op_sel_hi:[1,0,1]
	v_add_f32_dpp v238, v238, v238 quad_perm:[2,3,0,1] row_mask:0xf bank_mask:0xf bound_ctrl:1
	ds_write_b32 v49, v238 offset:1280
	ds_read_b128 v[224:227], v51 offset:13056
	s_waitcnt lgkmcnt(7)
	v_pk_mul_f32 v[232:233], v[28:29], v[36:37]
	v_pk_fma_f32 v[232:233], v[26:27], v[34:35], v[232:233]
	ds_read_b128 v[64:67], v51 offset:12544
	ds_read_b128 v[68:71], v51 offset:12800
	v_add_f32_e32 v234, v232, v233
	v_pk_mul_f32 v[236:237], v[24:25], v[36:37]
	v_pk_fma_f32 v[236:237], v[22:23], v[34:35], v[236:237]
	v_add_f32_dpp v234, v234, v234 quad_perm:[1,0,3,2] row_mask:0xf bank_mask:0xf bound_ctrl:1
	s_waitcnt lgkmcnt(6)
	v_pk_mul_f32 v[228:229], v[18:19], v[34:35]
	v_add_f32_e32 v238, v236, v237
	v_add_f32_dpp v234, v234, v234 quad_perm:[2,3,0,1] row_mask:0xf bank_mask:0xf bound_ctrl:1
	v_pk_mul_f32 v[230:231], v[20:21], v[36:37]
	v_pk_fma_f32 v[56:57], v[14:15], v[240:241], v[228:229] op_sel_hi:[1,0,1]
	v_add_f32_dpp v234, v234, v234 row_half_mirror row_mask:0xf bank_mask:0xf bound_ctrl:1
	v_pk_fma_f32 v[54:55], v[16:17], v[240:241], v[230:231] op_sel_hi:[1,0,1]
	v_add_f32_dpp v238, v238, v238 quad_perm:[1,0,3,2] row_mask:0xf bank_mask:0xf bound_ctrl:1
	v_add_f32_dpp v234, v234, v234 row_mirror row_mask:0xf bank_mask:0xf bound_ctrl:1
	ds_read_b32 v242, v62 offset:13568
	ds_read_b128 v[30:33], v51 offset:13312
	ds_read_b128 v[22:25], v51 offset:12288
	s_waitcnt lgkmcnt(8)
	v_pk_fma_f32 v[36:37], v[12:13], v[234:235], v[54:55] op_sel_hi:[1,0,1]
	v_pk_fma_f32 v[34:35], v[10:11], v[234:235], v[56:57] op_sel_hi:[1,0,1]
	v_add_f32_dpp v238, v238, v238 quad_perm:[2,3,0,1] row_mask:0xf bank_mask:0xf bound_ctrl:1
	ds_write_b32 v49, v238 offset:1536
	ds_read_b128 v[26:29], v51 offset:14592
	s_waitcnt lgkmcnt(7)
	v_pk_mul_f32 v[232:233], v[226:227], v[36:37]
	v_pk_fma_f32 v[232:233], v[224:225], v[34:35], v[232:233]
	ds_read_b128 v[18:21], v51 offset:14080
	ds_read_b128 v[14:17], v51 offset:14336
	v_add_f32_e32 v234, v232, v233
	v_pk_mul_f32 v[236:237], v[8:9], v[36:37]
	v_pk_fma_f32 v[236:237], v[6:7], v[34:35], v[236:237]
	v_add_f32_dpp v234, v234, v234 quad_perm:[1,0,3,2] row_mask:0xf bank_mask:0xf bound_ctrl:1
	s_waitcnt lgkmcnt(6)
	v_pk_mul_f32 v[228:229], v[64:65], v[34:35]
	v_add_f32_e32 v238, v236, v237
	v_add_f32_dpp v234, v234, v234 quad_perm:[2,3,0,1] row_mask:0xf bank_mask:0xf bound_ctrl:1
	v_pk_mul_f32 v[230:231], v[66:67], v[36:37]
	v_pk_fma_f32 v[56:57], v[68:69], v[242:243], v[228:229] op_sel_hi:[1,0,1]
	v_add_f32_dpp v234, v234, v234 row_half_mirror row_mask:0xf bank_mask:0xf bound_ctrl:1
	v_pk_fma_f32 v[54:55], v[70:71], v[242:243], v[230:231] op_sel_hi:[1,0,1]
	v_add_f32_dpp v238, v238, v238 quad_perm:[1,0,3,2] row_mask:0xf bank_mask:0xf bound_ctrl:1
	v_add_f32_dpp v234, v234, v234 row_mirror row_mask:0xf bank_mask:0xf bound_ctrl:1
	ds_read_b32 v240, v62 offset:15104
	ds_read_b128 v[10:13], v51 offset:14848
	ds_read_b128 v[6:9], v51 offset:13824
	s_waitcnt lgkmcnt(8)
	v_pk_fma_f32 v[36:37], v[32:33], v[234:235], v[54:55] op_sel_hi:[1,0,1]
	v_pk_fma_f32 v[34:35], v[30:31], v[234:235], v[56:57] op_sel_hi:[1,0,1]
	v_add_f32_dpp v238, v238, v238 quad_perm:[2,3,0,1] row_mask:0xf bank_mask:0xf bound_ctrl:1
	ds_write_b32 v49, v238 offset:1792
	ds_read_b128 v[224:227], v51 offset:16128
	s_waitcnt lgkmcnt(7)
	v_pk_mul_f32 v[232:233], v[28:29], v[36:37]
	v_pk_fma_f32 v[232:233], v[26:27], v[34:35], v[232:233]
	ds_read_b128 v[64:67], v51 offset:15616
	ds_read_b128 v[68:71], v51 offset:15872
	v_add_f32_e32 v234, v232, v233
	v_pk_mul_f32 v[236:237], v[24:25], v[36:37]
	v_pk_fma_f32 v[236:237], v[22:23], v[34:35], v[236:237]
	v_add_f32_dpp v234, v234, v234 quad_perm:[1,0,3,2] row_mask:0xf bank_mask:0xf bound_ctrl:1
	s_waitcnt lgkmcnt(6)
	v_pk_mul_f32 v[228:229], v[18:19], v[34:35]
	v_add_f32_e32 v238, v236, v237
	v_add_f32_dpp v234, v234, v234 quad_perm:[2,3,0,1] row_mask:0xf bank_mask:0xf bound_ctrl:1
	v_pk_mul_f32 v[230:231], v[20:21], v[36:37]
	v_pk_fma_f32 v[56:57], v[14:15], v[240:241], v[228:229] op_sel_hi:[1,0,1]
	v_add_f32_dpp v234, v234, v234 row_half_mirror row_mask:0xf bank_mask:0xf bound_ctrl:1
	v_pk_fma_f32 v[54:55], v[16:17], v[240:241], v[230:231] op_sel_hi:[1,0,1]
	v_add_f32_dpp v238, v238, v238 quad_perm:[1,0,3,2] row_mask:0xf bank_mask:0xf bound_ctrl:1
	v_add_f32_dpp v234, v234, v234 row_mirror row_mask:0xf bank_mask:0xf bound_ctrl:1
	ds_read_b32 v242, v62 offset:16640
	ds_read_b128 v[30:33], v51 offset:16384
	ds_read_b128 v[22:25], v51 offset:15360
	s_waitcnt lgkmcnt(8)
	v_pk_fma_f32 v[36:37], v[12:13], v[234:235], v[54:55] op_sel_hi:[1,0,1]
	v_pk_fma_f32 v[34:35], v[10:11], v[234:235], v[56:57] op_sel_hi:[1,0,1]
	v_add_f32_dpp v238, v238, v238 quad_perm:[2,3,0,1] row_mask:0xf bank_mask:0xf bound_ctrl:1
	ds_write_b32 v49, v238 offset:2048
	ds_read_b128 v[26:29], v51 offset:17664
	s_waitcnt lgkmcnt(7)
	v_pk_mul_f32 v[232:233], v[226:227], v[36:37]
	v_pk_fma_f32 v[232:233], v[224:225], v[34:35], v[232:233]
	ds_read_b128 v[18:21], v51 offset:17152
	ds_read_b128 v[14:17], v51 offset:17408
	v_add_f32_e32 v234, v232, v233
	v_pk_mul_f32 v[236:237], v[8:9], v[36:37]
	v_pk_fma_f32 v[236:237], v[6:7], v[34:35], v[236:237]
	v_add_f32_dpp v234, v234, v234 quad_perm:[1,0,3,2] row_mask:0xf bank_mask:0xf bound_ctrl:1
	s_waitcnt lgkmcnt(6)
	v_pk_mul_f32 v[228:229], v[64:65], v[34:35]
	v_add_f32_e32 v238, v236, v237
	v_add_f32_dpp v234, v234, v234 quad_perm:[2,3,0,1] row_mask:0xf bank_mask:0xf bound_ctrl:1
	v_pk_mul_f32 v[230:231], v[66:67], v[36:37]
	v_pk_fma_f32 v[56:57], v[68:69], v[242:243], v[228:229] op_sel_hi:[1,0,1]
	v_add_f32_dpp v234, v234, v234 row_half_mirror row_mask:0xf bank_mask:0xf bound_ctrl:1
	v_pk_fma_f32 v[54:55], v[70:71], v[242:243], v[230:231] op_sel_hi:[1,0,1]
	v_add_f32_dpp v238, v238, v238 quad_perm:[1,0,3,2] row_mask:0xf bank_mask:0xf bound_ctrl:1
	v_add_f32_dpp v234, v234, v234 row_mirror row_mask:0xf bank_mask:0xf bound_ctrl:1
	ds_read_b32 v240, v62 offset:18176
	ds_read_b128 v[10:13], v51 offset:17920
	ds_read_b128 v[6:9], v51 offset:16896
	s_waitcnt lgkmcnt(8)
	v_pk_fma_f32 v[36:37], v[32:33], v[234:235], v[54:55] op_sel_hi:[1,0,1]
	v_pk_fma_f32 v[34:35], v[30:31], v[234:235], v[56:57] op_sel_hi:[1,0,1]
	v_add_f32_dpp v238, v238, v238 quad_perm:[2,3,0,1] row_mask:0xf bank_mask:0xf bound_ctrl:1
	ds_write_b32 v49, v238 offset:2304
	ds_read_b128 v[224:227], v51 offset:19200
	s_waitcnt lgkmcnt(7)
	v_pk_mul_f32 v[232:233], v[28:29], v[36:37]
	v_pk_fma_f32 v[232:233], v[26:27], v[34:35], v[232:233]
	ds_read_b128 v[64:67], v51 offset:18688
	ds_read_b128 v[68:71], v51 offset:18944
	v_add_f32_e32 v234, v232, v233
	v_pk_mul_f32 v[236:237], v[24:25], v[36:37]
	v_pk_fma_f32 v[236:237], v[22:23], v[34:35], v[236:237]
	v_add_f32_dpp v234, v234, v234 quad_perm:[1,0,3,2] row_mask:0xf bank_mask:0xf bound_ctrl:1
	s_waitcnt lgkmcnt(6)
	v_pk_mul_f32 v[228:229], v[18:19], v[34:35]
	v_add_f32_e32 v238, v236, v237
	v_add_f32_dpp v234, v234, v234 quad_perm:[2,3,0,1] row_mask:0xf bank_mask:0xf bound_ctrl:1
	v_pk_mul_f32 v[230:231], v[20:21], v[36:37]
	v_pk_fma_f32 v[56:57], v[14:15], v[240:241], v[228:229] op_sel_hi:[1,0,1]
	v_add_f32_dpp v234, v234, v234 row_half_mirror row_mask:0xf bank_mask:0xf bound_ctrl:1
	v_pk_fma_f32 v[54:55], v[16:17], v[240:241], v[230:231] op_sel_hi:[1,0,1]
	v_add_f32_dpp v238, v238, v238 quad_perm:[1,0,3,2] row_mask:0xf bank_mask:0xf bound_ctrl:1
	v_add_f32_dpp v234, v234, v234 row_mirror row_mask:0xf bank_mask:0xf bound_ctrl:1
	ds_read_b32 v242, v62 offset:19712
	ds_read_b128 v[30:33], v51 offset:19456
	ds_read_b128 v[22:25], v51 offset:18432
	s_waitcnt lgkmcnt(8)
	v_pk_fma_f32 v[36:37], v[12:13], v[234:235], v[54:55] op_sel_hi:[1,0,1]
	v_pk_fma_f32 v[34:35], v[10:11], v[234:235], v[56:57] op_sel_hi:[1,0,1]
	v_add_f32_dpp v238, v238, v238 quad_perm:[2,3,0,1] row_mask:0xf bank_mask:0xf bound_ctrl:1
	ds_write_b32 v49, v238 offset:2560
	ds_read_b128 v[26:29], v51 offset:20736
	s_waitcnt lgkmcnt(7)
	v_pk_mul_f32 v[232:233], v[226:227], v[36:37]
	v_pk_fma_f32 v[232:233], v[224:225], v[34:35], v[232:233]
	ds_read_b128 v[18:21], v51 offset:20224
	ds_read_b128 v[14:17], v51 offset:20480
	v_add_f32_e32 v234, v232, v233
	v_pk_mul_f32 v[236:237], v[8:9], v[36:37]
	v_pk_fma_f32 v[236:237], v[6:7], v[34:35], v[236:237]
	v_add_f32_dpp v234, v234, v234 quad_perm:[1,0,3,2] row_mask:0xf bank_mask:0xf bound_ctrl:1
	s_waitcnt lgkmcnt(6)
	v_pk_mul_f32 v[228:229], v[64:65], v[34:35]
	v_add_f32_e32 v238, v236, v237
	v_add_f32_dpp v234, v234, v234 quad_perm:[2,3,0,1] row_mask:0xf bank_mask:0xf bound_ctrl:1
	v_pk_mul_f32 v[230:231], v[66:67], v[36:37]
	v_pk_fma_f32 v[56:57], v[68:69], v[242:243], v[228:229] op_sel_hi:[1,0,1]
	v_add_f32_dpp v234, v234, v234 row_half_mirror row_mask:0xf bank_mask:0xf bound_ctrl:1
	v_pk_fma_f32 v[54:55], v[70:71], v[242:243], v[230:231] op_sel_hi:[1,0,1]
	v_add_f32_dpp v238, v238, v238 quad_perm:[1,0,3,2] row_mask:0xf bank_mask:0xf bound_ctrl:1
	v_add_f32_dpp v234, v234, v234 row_mirror row_mask:0xf bank_mask:0xf bound_ctrl:1
	ds_read_b32 v240, v62 offset:21248
	ds_read_b128 v[10:13], v51 offset:20992
	ds_read_b128 v[6:9], v51 offset:19968
	s_waitcnt lgkmcnt(8)
	v_pk_fma_f32 v[36:37], v[32:33], v[234:235], v[54:55] op_sel_hi:[1,0,1]
	v_pk_fma_f32 v[34:35], v[30:31], v[234:235], v[56:57] op_sel_hi:[1,0,1]
	v_add_f32_dpp v238, v238, v238 quad_perm:[2,3,0,1] row_mask:0xf bank_mask:0xf bound_ctrl:1
	ds_write_b32 v49, v238 offset:2816
	ds_read_b128 v[224:227], v51 offset:22272
	s_waitcnt lgkmcnt(7)
	v_pk_mul_f32 v[232:233], v[28:29], v[36:37]
	v_pk_fma_f32 v[232:233], v[26:27], v[34:35], v[232:233]
	ds_read_b128 v[64:67], v51 offset:21760
	ds_read_b128 v[68:71], v51 offset:22016
	v_add_f32_e32 v234, v232, v233
	v_pk_mul_f32 v[236:237], v[24:25], v[36:37]
	v_pk_fma_f32 v[236:237], v[22:23], v[34:35], v[236:237]
	v_add_f32_dpp v234, v234, v234 quad_perm:[1,0,3,2] row_mask:0xf bank_mask:0xf bound_ctrl:1
	s_waitcnt lgkmcnt(6)
	v_pk_mul_f32 v[228:229], v[18:19], v[34:35]
	v_add_f32_e32 v238, v236, v237
	v_add_f32_dpp v234, v234, v234 quad_perm:[2,3,0,1] row_mask:0xf bank_mask:0xf bound_ctrl:1
	v_pk_mul_f32 v[230:231], v[20:21], v[36:37]
	v_pk_fma_f32 v[56:57], v[14:15], v[240:241], v[228:229] op_sel_hi:[1,0,1]
	v_add_f32_dpp v234, v234, v234 row_half_mirror row_mask:0xf bank_mask:0xf bound_ctrl:1
	v_pk_fma_f32 v[54:55], v[16:17], v[240:241], v[230:231] op_sel_hi:[1,0,1]
	v_add_f32_dpp v238, v238, v238 quad_perm:[1,0,3,2] row_mask:0xf bank_mask:0xf bound_ctrl:1
	v_add_f32_dpp v234, v234, v234 row_mirror row_mask:0xf bank_mask:0xf bound_ctrl:1
	ds_read_b32 v242, v62 offset:22784
	ds_read_b128 v[30:33], v51 offset:22528
	ds_read_b128 v[22:25], v51 offset:21504
	s_waitcnt lgkmcnt(8)
	v_pk_fma_f32 v[36:37], v[12:13], v[234:235], v[54:55] op_sel_hi:[1,0,1]
	v_pk_fma_f32 v[34:35], v[10:11], v[234:235], v[56:57] op_sel_hi:[1,0,1]
	v_add_f32_dpp v238, v238, v238 quad_perm:[2,3,0,1] row_mask:0xf bank_mask:0xf bound_ctrl:1
	ds_write_b32 v49, v238 offset:3072
	ds_read_b128 v[26:29], v51 offset:23808
	s_waitcnt lgkmcnt(7)
	v_pk_mul_f32 v[232:233], v[226:227], v[36:37]
	v_pk_fma_f32 v[232:233], v[224:225], v[34:35], v[232:233]
	ds_read_b128 v[18:21], v51 offset:23296
	ds_read_b128 v[14:17], v51 offset:23552
	v_add_f32_e32 v234, v232, v233
	v_pk_mul_f32 v[236:237], v[8:9], v[36:37]
	v_pk_fma_f32 v[236:237], v[6:7], v[34:35], v[236:237]
	v_add_f32_dpp v234, v234, v234 quad_perm:[1,0,3,2] row_mask:0xf bank_mask:0xf bound_ctrl:1
	s_waitcnt lgkmcnt(6)
	v_pk_mul_f32 v[228:229], v[64:65], v[34:35]
	v_add_f32_e32 v238, v236, v237
	v_add_f32_dpp v234, v234, v234 quad_perm:[2,3,0,1] row_mask:0xf bank_mask:0xf bound_ctrl:1
	v_pk_mul_f32 v[230:231], v[66:67], v[36:37]
	v_pk_fma_f32 v[56:57], v[68:69], v[242:243], v[228:229] op_sel_hi:[1,0,1]
	v_add_f32_dpp v234, v234, v234 row_half_mirror row_mask:0xf bank_mask:0xf bound_ctrl:1
	v_pk_fma_f32 v[54:55], v[70:71], v[242:243], v[230:231] op_sel_hi:[1,0,1]
	v_add_f32_dpp v238, v238, v238 quad_perm:[1,0,3,2] row_mask:0xf bank_mask:0xf bound_ctrl:1
	v_add_f32_dpp v234, v234, v234 row_mirror row_mask:0xf bank_mask:0xf bound_ctrl:1
	ds_read_b32 v240, v62 offset:24320
	ds_read_b128 v[10:13], v51 offset:24064
	ds_read_b128 v[6:9], v51 offset:23040
	s_waitcnt lgkmcnt(8)
	v_pk_fma_f32 v[36:37], v[32:33], v[234:235], v[54:55] op_sel_hi:[1,0,1]
	v_pk_fma_f32 v[34:35], v[30:31], v[234:235], v[56:57] op_sel_hi:[1,0,1]
	v_add_f32_dpp v238, v238, v238 quad_perm:[2,3,0,1] row_mask:0xf bank_mask:0xf bound_ctrl:1
	ds_write_b32 v49, v238 offset:3328
	s_waitcnt lgkmcnt(6)
	v_pk_mul_f32 v[232:233], v[28:29], v[36:37]
	v_pk_fma_f32 v[232:233], v[26:27], v[34:35], v[232:233]
	v_add_f32_e32 v234, v232, v233
	v_pk_mul_f32 v[236:237], v[24:25], v[36:37]
	v_pk_fma_f32 v[236:237], v[22:23], v[34:35], v[236:237]
	v_add_f32_dpp v234, v234, v234 quad_perm:[1,0,3,2] row_mask:0xf bank_mask:0xf bound_ctrl:1
	s_waitcnt lgkmcnt(3)
	v_pk_mul_f32 v[228:229], v[18:19], v[34:35]
	v_add_f32_e32 v238, v236, v237
	v_add_f32_dpp v234, v234, v234 quad_perm:[2,3,0,1] row_mask:0xf bank_mask:0xf bound_ctrl:1
	v_pk_mul_f32 v[230:231], v[20:21], v[36:37]
	v_pk_fma_f32 v[56:57], v[14:15], v[240:241], v[228:229] op_sel_hi:[1,0,1]
	v_add_f32_dpp v234, v234, v234 row_half_mirror row_mask:0xf bank_mask:0xf bound_ctrl:1
	v_pk_fma_f32 v[54:55], v[16:17], v[240:241], v[230:231] op_sel_hi:[1,0,1]
	v_add_f32_dpp v238, v238, v238 quad_perm:[1,0,3,2] row_mask:0xf bank_mask:0xf bound_ctrl:1
	v_add_f32_dpp v234, v234, v234 row_mirror row_mask:0xf bank_mask:0xf bound_ctrl:1
	s_waitcnt lgkmcnt(2)
	v_pk_fma_f32 v[36:37], v[12:13], v[234:235], v[54:55] op_sel_hi:[1,0,1]
	v_pk_fma_f32 v[34:35], v[10:11], v[234:235], v[56:57] op_sel_hi:[1,0,1]
	v_add_f32_dpp v238, v238, v238 quad_perm:[2,3,0,1] row_mask:0xf bank_mask:0xf bound_ctrl:1
	ds_write_b32 v49, v238 offset:3584
	v_pk_mul_f32 v[236:237], v[8:9], v[36:37]
	v_pk_fma_f32 v[236:237], v[6:7], v[34:35], v[236:237]
	v_add_f32_e32 v238, v236, v237
	s_nop 1
	v_add_f32_dpp v52, v238, v238 quad_perm:[1,0,3,2] row_mask:0xf bank_mask:0xf bound_ctrl:1
	s_nop 1
	v_mov_b32_dpp v64, v52 quad_perm:[2,3,0,1] row_mask:0xf bank_mask:0xf bound_ctrl:1

.LBB0_1675:
	s_or_b64 exec, exec, s[22:23]
	v_lshl_add_u64 v[6:7], s[14:15], 0, v[0:1]
	v_mad_u64_u32 v[10:11], s[2:3], v188, s51, v[6:7]
	v_mad_i32_i24 v11, v189, s51, v11
	s_mov_b64 s[92:93], 0x3000
	v_mov_b64_e32 v[84:85], v[10:11]
	global_load_dwordx4 v[20:23], v[84:85], off
	v_lshl_add_u64 v[84:85], v[84:85], 0, s[92:93]
	global_load_dwordx4 v[24:27], v[84:85], off
	v_lshl_add_u64 v[84:85], v[84:85], 0, s[92:93]
	global_load_dwordx4 v[28:31], v[84:85], off
	v_lshl_add_u64 v[84:85], v[84:85], 0, s[92:93]
	global_load_dwordx4 v[32:35], v[84:85], off
	v_lshl_add_u64 v[84:85], v[84:85], 0, s[92:93]
	global_load_dwordx4 v[36:39], v[84:85], off
	v_lshl_add_u64 v[84:85], v[84:85], 0, s[92:93]
	global_load_dwordx4 v[40:43], v[84:85], off
	v_lshl_add_u64 v[84:85], v[84:85], 0, s[92:93]
	global_load_dwordx4 v[44:47], v[84:85], off
	v_lshl_add_u64 v[84:85], v[84:85], 0, s[92:93]
	global_load_dwordx4 v[48:51], v[84:85], off
	v_lshl_add_u64 v[84:85], v[84:85], 0, s[92:93]
	global_load_dwordx4 v[52:55], v[84:85], off
	v_lshl_add_u64 v[84:85], v[84:85], 0, s[92:93]
	global_load_dwordx4 v[56:59], v[84:85], off
	v_lshl_add_u64 v[84:85], v[84:85], 0, s[92:93]
	global_load_dwordx4 v[60:63], v[84:85], off
	v_lshl_add_u64 v[84:85], v[84:85], 0, s[92:93]
	global_load_dwordx4 v[64:67], v[84:85], off
	v_lshl_add_u64 v[84:85], v[84:85], 0, s[92:93]
	global_load_dwordx4 v[68:71], v[84:85], off
	v_lshl_add_u64 v[84:85], v[84:85], 0, s[92:93]
	global_load_dwordx4 v[72:75], v[84:85], off
	v_lshl_add_u64 v[84:85], v[84:85], 0, s[92:93]
	global_load_dwordx4 v[76:79], v[84:85], off
	v_lshl_add_u64 v[84:85], v[84:85], 0, s[92:93]
	global_load_dwordx4 v[80:83], v[84:85], off
	s_movk_i32 s2, 0x6000
	s_waitcnt vmcnt(15)
	v_mov_b64_e32 v[6:7], v[20:21]
	v_mov_b64_e32 v[8:9], v[22:23]
	v_pk_mul_f32 v[8:9], v[198:199], v[8:9]
	v_pk_mul_f32 v[6:7], v[200:201], v[6:7]
	v_and_b32_sdwa v12, v8, v202 dst_sel:DWORD dst_unused:UNUSED_PAD src0_sel:WORD_1 src1_sel:DWORD
	v_and_b32_sdwa v13, v6, v202 dst_sel:DWORD dst_unused:UNUSED_PAD src0_sel:WORD_1 src1_sel:DWORD
	v_add3_u32 v8, v8, v12, s85
	v_and_b32_sdwa v12, v9, v202 dst_sel:DWORD dst_unused:UNUSED_PAD src0_sel:WORD_1 src1_sel:DWORD
	v_add3_u32 v6, v6, v13, s85
	v_and_b32_sdwa v13, v7, v202 dst_sel:DWORD dst_unused:UNUSED_PAD src0_sel:WORD_1 src1_sel:DWORD
	v_add3_u32 v9, v9, v12, s85
	v_add3_u32 v7, v7, v13, s85
	v_and_b32_e32 v9, 0xffff0000, v9
	v_and_b32_e32 v7, 0xffff0000, v7
	v_or_b32_sdwa v13, v9, v8 dst_sel:DWORD dst_unused:UNUSED_PAD src0_sel:DWORD src1_sel:WORD_1
	v_lshlrev_b64 v[8:9], 12, v[188:189]
	v_or_b32_sdwa v12, v7, v6 dst_sel:DWORD dst_unused:UNUSED_PAD src0_sel:DWORD src1_sel:WORD_1
	v_lshl_add_u64 v[14:15], s[10:11], 0, v[8:9]
	v_lshlrev_b32_e32 v6, 1, v217
	v_mov_b32_e32 v7, v1
	v_lshl_add_u64 v[14:15], v[14:15], 0, v[6:7]
	global_store_dwordx2 v[14:15], v[12:13], off offset:2048
	v_add_co_u32_e32 v12, vcc, s51, v10
	s_nop 1
	v_addc_co_u32_e32 v13, vcc, 0, v11, vcc
	s_waitcnt vmcnt(15)
	v_mov_b64_e32 v[12:13], v[24:25]
	v_mov_b64_e32 v[14:15], v[26:27]
	v_pk_mul_f32 v[14:15], v[194:195], v[14:15]
	v_pk_mul_f32 v[12:13], v[196:197], v[12:13]
	v_and_b32_sdwa v16, v14, v202 dst_sel:DWORD dst_unused:UNUSED_PAD src0_sel:WORD_1 src1_sel:DWORD
	v_and_b32_sdwa v17, v12, v202 dst_sel:DWORD dst_unused:UNUSED_PAD src0_sel:WORD_1 src1_sel:DWORD
	v_add3_u32 v14, v14, v16, s85
	v_and_b32_sdwa v16, v15, v202 dst_sel:DWORD dst_unused:UNUSED_PAD src0_sel:WORD_1 src1_sel:DWORD
	v_add3_u32 v12, v12, v17, s85
	v_and_b32_sdwa v17, v13, v202 dst_sel:DWORD dst_unused:UNUSED_PAD src0_sel:WORD_1 src1_sel:DWORD
	v_add3_u32 v15, v15, v16, s85
	v_add3_u32 v13, v13, v17, s85
	v_and_b32_e32 v15, 0xffff0000, v15
	v_and_b32_e32 v16, 0xffff0000, v13
	v_or_b32_sdwa v13, v15, v14 dst_sel:DWORD dst_unused:UNUSED_PAD src0_sel:DWORD src1_sel:WORD_1
	v_or_b32_e32 v14, 0x1000, v8
	v_mov_b32_e32 v15, v9
	v_lshl_add_u64 v[14:15], s[10:11], 0, v[14:15]
	v_or_b32_sdwa v12, v16, v12 dst_sel:DWORD dst_unused:UNUSED_PAD src0_sel:DWORD src1_sel:WORD_1
	v_lshl_add_u64 v[14:15], v[14:15], 0, v[6:7]
	global_store_dwordx2 v[14:15], v[12:13], off offset:2048
	v_add_co_u32_e32 v12, vcc, s2, v10
	s_mov_b32 s2, 0x9000
	s_nop 0
	v_addc_co_u32_e32 v13, vcc, 0, v11, vcc
	s_waitcnt vmcnt(15)
	v_mov_b64_e32 v[12:13], v[28:29]
	v_mov_b64_e32 v[14:15], v[30:31]
	v_pk_mul_f32 v[14:15], v[190:191], v[14:15]
	v_pk_mul_f32 v[12:13], v[192:193], v[12:13]
	v_and_b32_sdwa v16, v14, v202 dst_sel:DWORD dst_unused:UNUSED_PAD src0_sel:WORD_1 src1_sel:DWORD
	v_and_b32_sdwa v17, v12, v202 dst_sel:DWORD dst_unused:UNUSED_PAD src0_sel:WORD_1 src1_sel:DWORD
	v_add3_u32 v14, v14, v16, s85
	v_and_b32_sdwa v16, v15, v202 dst_sel:DWORD dst_unused:UNUSED_PAD src0_sel:WORD_1 src1_sel:DWORD
	v_add3_u32 v12, v12, v17, s85
	v_and_b32_sdwa v17, v13, v202 dst_sel:DWORD dst_unused:UNUSED_PAD src0_sel:WORD_1 src1_sel:DWORD
	v_add3_u32 v15, v15, v16, s85
	v_add3_u32 v13, v13, v17, s85
	v_and_b32_e32 v15, 0xffff0000, v15
	v_and_b32_e32 v16, 0xffff0000, v13
	v_or_b32_sdwa v13, v15, v14 dst_sel:DWORD dst_unused:UNUSED_PAD src0_sel:DWORD src1_sel:WORD_1
	v_or_b32_e32 v14, 0x2000, v8
	v_mov_b32_e32 v15, v9
	v_lshl_add_u64 v[14:15], s[10:11], 0, v[14:15]
	v_or_b32_sdwa v12, v16, v12 dst_sel:DWORD dst_unused:UNUSED_PAD src0_sel:DWORD src1_sel:WORD_1
	v_lshl_add_u64 v[14:15], v[14:15], 0, v[6:7]
	global_store_dwordx2 v[14:15], v[12:13], off offset:2048
	v_add_co_u32_e32 v12, vcc, s2, v10
	s_mov_b32 s2, 0xc000
	s_nop 0
	v_addc_co_u32_e32 v13, vcc, 0, v11, vcc
	s_waitcnt vmcnt(15)
	v_mov_b64_e32 v[12:13], v[32:33]
	v_mov_b64_e32 v[14:15], v[34:35]
	v_pk_mul_f32 v[14:15], v[184:185], v[14:15]
	v_pk_mul_f32 v[12:13], v[186:187], v[12:13]
	v_and_b32_sdwa v16, v14, v202 dst_sel:DWORD dst_unused:UNUSED_PAD src0_sel:WORD_1 src1_sel:DWORD
	v_and_b32_sdwa v17, v12, v202 dst_sel:DWORD dst_unused:UNUSED_PAD src0_sel:WORD_1 src1_sel:DWORD
	v_add3_u32 v14, v14, v16, s85
	v_and_b32_sdwa v16, v15, v202 dst_sel:DWORD dst_unused:UNUSED_PAD src0_sel:WORD_1 src1_sel:DWORD
	v_add3_u32 v12, v12, v17, s85
	v_and_b32_sdwa v17, v13, v202 dst_sel:DWORD dst_unused:UNUSED_PAD src0_sel:WORD_1 src1_sel:DWORD
	v_add3_u32 v15, v15, v16, s85
	v_add3_u32 v13, v13, v17, s85
	v_and_b32_e32 v15, 0xffff0000, v15
	v_and_b32_e32 v16, 0xffff0000, v13
	v_or_b32_sdwa v13, v15, v14 dst_sel:DWORD dst_unused:UNUSED_PAD src0_sel:DWORD src1_sel:WORD_1
	v_or_b32_e32 v14, 0x3000, v8
	v_mov_b32_e32 v15, v9
	v_lshl_add_u64 v[14:15], s[10:11], 0, v[14:15]
	v_or_b32_sdwa v12, v16, v12 dst_sel:DWORD dst_unused:UNUSED_PAD src0_sel:DWORD src1_sel:WORD_1
	v_lshl_add_u64 v[14:15], v[14:15], 0, v[6:7]
	global_store_dwordx2 v[14:15], v[12:13], off offset:2048
	v_add_co_u32_e32 v12, vcc, s2, v10
	s_mov_b32 s2, 0xf000
	s_nop 0
	v_addc_co_u32_e32 v13, vcc, 0, v11, vcc
	s_waitcnt vmcnt(15)
	v_mov_b64_e32 v[12:13], v[36:37]
	v_mov_b64_e32 v[14:15], v[38:39]
	v_pk_mul_f32 v[14:15], v[180:181], v[14:15]
	v_pk_mul_f32 v[12:13], v[182:183], v[12:13]
	v_and_b32_sdwa v16, v14, v202 dst_sel:DWORD dst_unused:UNUSED_PAD src0_sel:WORD_1 src1_sel:DWORD
	v_and_b32_sdwa v17, v12, v202 dst_sel:DWORD dst_unused:UNUSED_PAD src0_sel:WORD_1 src1_sel:DWORD
	v_add3_u32 v14, v14, v16, s85
	v_and_b32_sdwa v16, v15, v202 dst_sel:DWORD dst_unused:UNUSED_PAD src0_sel:WORD_1 src1_sel:DWORD
	v_add3_u32 v12, v12, v17, s85
	v_and_b32_sdwa v17, v13, v202 dst_sel:DWORD dst_unused:UNUSED_PAD src0_sel:WORD_1 src1_sel:DWORD
	v_add3_u32 v15, v15, v16, s85
	v_add3_u32 v13, v13, v17, s85
	v_and_b32_e32 v15, 0xffff0000, v15
	v_and_b32_e32 v16, 0xffff0000, v13
	v_or_b32_sdwa v13, v15, v14 dst_sel:DWORD dst_unused:UNUSED_PAD src0_sel:DWORD src1_sel:WORD_1
	v_or_b32_e32 v14, 0x4000, v8
	v_mov_b32_e32 v15, v9
	v_lshl_add_u64 v[14:15], s[10:11], 0, v[14:15]
	v_or_b32_sdwa v12, v16, v12 dst_sel:DWORD dst_unused:UNUSED_PAD src0_sel:DWORD src1_sel:WORD_1
	v_lshl_add_u64 v[14:15], v[14:15], 0, v[6:7]
	global_store_dwordx2 v[14:15], v[12:13], off offset:2048
	v_add_co_u32_e32 v12, vcc, s2, v10
	s_mov_b32 s2, 0x12000
	s_nop 0
	v_addc_co_u32_e32 v13, vcc, 0, v11, vcc
	s_waitcnt vmcnt(15)
	v_mov_b64_e32 v[12:13], v[40:41]
	v_mov_b64_e32 v[14:15], v[42:43]
	v_pk_mul_f32 v[14:15], v[176:177], v[14:15]
	v_pk_mul_f32 v[12:13], v[178:179], v[12:13]
	v_and_b32_sdwa v16, v14, v202 dst_sel:DWORD dst_unused:UNUSED_PAD src0_sel:WORD_1 src1_sel:DWORD
	v_and_b32_sdwa v17, v12, v202 dst_sel:DWORD dst_unused:UNUSED_PAD src0_sel:WORD_1 src1_sel:DWORD
	v_add3_u32 v14, v14, v16, s85
	v_and_b32_sdwa v16, v15, v202 dst_sel:DWORD dst_unused:UNUSED_PAD src0_sel:WORD_1 src1_sel:DWORD
	v_add3_u32 v12, v12, v17, s85
	v_and_b32_sdwa v17, v13, v202 dst_sel:DWORD dst_unused:UNUSED_PAD src0_sel:WORD_1 src1_sel:DWORD
	v_add3_u32 v15, v15, v16, s85
	v_add3_u32 v13, v13, v17, s85
	v_and_b32_e32 v15, 0xffff0000, v15
	v_and_b32_e32 v16, 0xffff0000, v13
	v_or_b32_sdwa v13, v15, v14 dst_sel:DWORD dst_unused:UNUSED_PAD src0_sel:DWORD src1_sel:WORD_1
	v_or_b32_e32 v14, 0x5000, v8
	v_mov_b32_e32 v15, v9
	v_lshl_add_u64 v[14:15], s[10:11], 0, v[14:15]
	v_or_b32_sdwa v12, v16, v12 dst_sel:DWORD dst_unused:UNUSED_PAD src0_sel:DWORD src1_sel:WORD_1
	v_lshl_add_u64 v[14:15], v[14:15], 0, v[6:7]
	global_store_dwordx2 v[14:15], v[12:13], off offset:2048
	v_add_co_u32_e32 v12, vcc, s2, v10
	s_mov_b32 s2, 0x15000
	s_nop 0
	v_addc_co_u32_e32 v13, vcc, 0, v11, vcc
	s_waitcnt vmcnt(15)
	v_mov_b64_e32 v[12:13], v[44:45]
	v_mov_b64_e32 v[14:15], v[46:47]
	v_pk_mul_f32 v[14:15], v[168:169], v[14:15]
	v_pk_mul_f32 v[12:13], v[174:175], v[12:13]
	v_and_b32_sdwa v16, v14, v202 dst_sel:DWORD dst_unused:UNUSED_PAD src0_sel:WORD_1 src1_sel:DWORD
	v_and_b32_sdwa v17, v12, v202 dst_sel:DWORD dst_unused:UNUSED_PAD src0_sel:WORD_1 src1_sel:DWORD
	v_add3_u32 v14, v14, v16, s85
	v_and_b32_sdwa v16, v15, v202 dst_sel:DWORD dst_unused:UNUSED_PAD src0_sel:WORD_1 src1_sel:DWORD
	v_add3_u32 v12, v12, v17, s85
	v_and_b32_sdwa v17, v13, v202 dst_sel:DWORD dst_unused:UNUSED_PAD src0_sel:WORD_1 src1_sel:DWORD
	v_add3_u32 v15, v15, v16, s85
	v_add3_u32 v13, v13, v17, s85
	v_and_b32_e32 v15, 0xffff0000, v15
	v_and_b32_e32 v16, 0xffff0000, v13
	v_or_b32_sdwa v13, v15, v14 dst_sel:DWORD dst_unused:UNUSED_PAD src0_sel:DWORD src1_sel:WORD_1
	v_or_b32_e32 v14, 0x6000, v8
	v_mov_b32_e32 v15, v9
	v_lshl_add_u64 v[14:15], s[10:11], 0, v[14:15]
	v_or_b32_sdwa v12, v16, v12 dst_sel:DWORD dst_unused:UNUSED_PAD src0_sel:DWORD src1_sel:WORD_1
	v_lshl_add_u64 v[14:15], v[14:15], 0, v[6:7]
	global_store_dwordx2 v[14:15], v[12:13], off offset:2048
	v_add_co_u32_e32 v12, vcc, s2, v10
	s_mov_b32 s2, 0x18000
	s_nop 0
	v_addc_co_u32_e32 v13, vcc, 0, v11, vcc
	s_waitcnt vmcnt(15)
	v_mov_b64_e32 v[12:13], v[48:49]
	v_mov_b64_e32 v[14:15], v[50:51]
	v_pk_mul_f32 v[14:15], v[164:165], v[14:15]
	v_pk_mul_f32 v[12:13], v[166:167], v[12:13]
	v_and_b32_sdwa v16, v14, v202 dst_sel:DWORD dst_unused:UNUSED_PAD src0_sel:WORD_1 src1_sel:DWORD
	v_and_b32_sdwa v17, v12, v202 dst_sel:DWORD dst_unused:UNUSED_PAD src0_sel:WORD_1 src1_sel:DWORD
	v_add3_u32 v14, v14, v16, s85
	v_and_b32_sdwa v16, v15, v202 dst_sel:DWORD dst_unused:UNUSED_PAD src0_sel:WORD_1 src1_sel:DWORD
	v_add3_u32 v12, v12, v17, s85
	v_and_b32_sdwa v17, v13, v202 dst_sel:DWORD dst_unused:UNUSED_PAD src0_sel:WORD_1 src1_sel:DWORD
	v_add3_u32 v15, v15, v16, s85
	v_add3_u32 v13, v13, v17, s85
	v_and_b32_e32 v15, 0xffff0000, v15
	v_and_b32_e32 v16, 0xffff0000, v13
	v_or_b32_sdwa v13, v15, v14 dst_sel:DWORD dst_unused:UNUSED_PAD src0_sel:DWORD src1_sel:WORD_1
	v_or_b32_e32 v14, 0x7000, v8
	v_mov_b32_e32 v15, v9
	v_lshl_add_u64 v[14:15], s[10:11], 0, v[14:15]
	v_or_b32_sdwa v12, v16, v12 dst_sel:DWORD dst_unused:UNUSED_PAD src0_sel:DWORD src1_sel:WORD_1
	v_lshl_add_u64 v[14:15], v[14:15], 0, v[6:7]
	global_store_dwordx2 v[14:15], v[12:13], off offset:2048
	v_add_co_u32_e32 v12, vcc, s2, v10
	s_mov_b32 s2, 0x1b000
	s_nop 0
	v_addc_co_u32_e32 v13, vcc, 0, v11, vcc
	s_waitcnt vmcnt(15)
	v_mov_b64_e32 v[12:13], v[52:53]
	v_mov_b64_e32 v[14:15], v[54:55]
	v_pk_mul_f32 v[14:15], v[160:161], v[14:15]
	v_pk_mul_f32 v[12:13], v[162:163], v[12:13]
	v_and_b32_sdwa v16, v14, v202 dst_sel:DWORD dst_unused:UNUSED_PAD src0_sel:WORD_1 src1_sel:DWORD
	v_and_b32_sdwa v17, v12, v202 dst_sel:DWORD dst_unused:UNUSED_PAD src0_sel:WORD_1 src1_sel:DWORD
	v_add3_u32 v14, v14, v16, s85
	v_and_b32_sdwa v16, v15, v202 dst_sel:DWORD dst_unused:UNUSED_PAD src0_sel:WORD_1 src1_sel:DWORD
	v_add3_u32 v12, v12, v17, s85
	v_and_b32_sdwa v17, v13, v202 dst_sel:DWORD dst_unused:UNUSED_PAD src0_sel:WORD_1 src1_sel:DWORD
	v_add3_u32 v15, v15, v16, s85
	v_add3_u32 v13, v13, v17, s85
	v_and_b32_e32 v15, 0xffff0000, v15
	v_and_b32_e32 v16, 0xffff0000, v13
	v_or_b32_sdwa v13, v15, v14 dst_sel:DWORD dst_unused:UNUSED_PAD src0_sel:DWORD src1_sel:WORD_1
	v_or_b32_e32 v14, 0x8000, v8
	v_mov_b32_e32 v15, v9
	v_lshl_add_u64 v[14:15], s[10:11], 0, v[14:15]
	v_or_b32_sdwa v12, v16, v12 dst_sel:DWORD dst_unused:UNUSED_PAD src0_sel:DWORD src1_sel:WORD_1
	v_lshl_add_u64 v[14:15], v[14:15], 0, v[6:7]
	global_store_dwordx2 v[14:15], v[12:13], off offset:2048
	v_add_co_u32_e32 v12, vcc, s2, v10
	s_mov_b32 s2, 0x1e000
	s_nop 0
	v_addc_co_u32_e32 v13, vcc, 0, v11, vcc
	s_waitcnt vmcnt(15)
	v_mov_b64_e32 v[12:13], v[56:57]
	v_mov_b64_e32 v[14:15], v[58:59]
	v_pk_mul_f32 v[14:15], v[156:157], v[14:15]
	v_pk_mul_f32 v[12:13], v[158:159], v[12:13]
	v_and_b32_sdwa v16, v14, v202 dst_sel:DWORD dst_unused:UNUSED_PAD src0_sel:WORD_1 src1_sel:DWORD
	v_and_b32_sdwa v17, v12, v202 dst_sel:DWORD dst_unused:UNUSED_PAD src0_sel:WORD_1 src1_sel:DWORD
	v_add3_u32 v14, v14, v16, s85
	v_and_b32_sdwa v16, v15, v202 dst_sel:DWORD dst_unused:UNUSED_PAD src0_sel:WORD_1 src1_sel:DWORD
	v_add3_u32 v12, v12, v17, s85
	v_and_b32_sdwa v17, v13, v202 dst_sel:DWORD dst_unused:UNUSED_PAD src0_sel:WORD_1 src1_sel:DWORD
	v_add3_u32 v15, v15, v16, s85
	v_add3_u32 v13, v13, v17, s85
	v_and_b32_e32 v15, 0xffff0000, v15
	v_and_b32_e32 v16, 0xffff0000, v13
	v_or_b32_sdwa v13, v15, v14 dst_sel:DWORD dst_unused:UNUSED_PAD src0_sel:DWORD src1_sel:WORD_1
	v_or_b32_e32 v14, 0x9000, v8
	v_mov_b32_e32 v15, v9
	v_lshl_add_u64 v[14:15], s[10:11], 0, v[14:15]
	v_or_b32_sdwa v12, v16, v12 dst_sel:DWORD dst_unused:UNUSED_PAD src0_sel:DWORD src1_sel:WORD_1
	v_lshl_add_u64 v[14:15], v[14:15], 0, v[6:7]
	global_store_dwordx2 v[14:15], v[12:13], off offset:2048
	v_add_co_u32_e32 v12, vcc, s2, v10
	s_mov_b32 s2, 0x21000
	s_nop 0
	v_addc_co_u32_e32 v13, vcc, 0, v11, vcc
	s_waitcnt vmcnt(15)
	v_mov_b64_e32 v[12:13], v[60:61]
	v_mov_b64_e32 v[14:15], v[62:63]
	v_pk_mul_f32 v[14:15], v[152:153], v[14:15]
	v_pk_mul_f32 v[12:13], v[154:155], v[12:13]
	v_and_b32_sdwa v16, v14, v202 dst_sel:DWORD dst_unused:UNUSED_PAD src0_sel:WORD_1 src1_sel:DWORD
	v_and_b32_sdwa v17, v12, v202 dst_sel:DWORD dst_unused:UNUSED_PAD src0_sel:WORD_1 src1_sel:DWORD
	v_add3_u32 v14, v14, v16, s85
	v_and_b32_sdwa v16, v15, v202 dst_sel:DWORD dst_unused:UNUSED_PAD src0_sel:WORD_1 src1_sel:DWORD
	v_add3_u32 v12, v12, v17, s85
	v_and_b32_sdwa v17, v13, v202 dst_sel:DWORD dst_unused:UNUSED_PAD src0_sel:WORD_1 src1_sel:DWORD
	v_add3_u32 v15, v15, v16, s85
	v_add3_u32 v13, v13, v17, s85
	v_and_b32_e32 v15, 0xffff0000, v15
	v_and_b32_e32 v16, 0xffff0000, v13
	v_or_b32_sdwa v13, v15, v14 dst_sel:DWORD dst_unused:UNUSED_PAD src0_sel:DWORD src1_sel:WORD_1
	v_or_b32_e32 v14, 0xa000, v8
	v_mov_b32_e32 v15, v9
	v_lshl_add_u64 v[14:15], s[10:11], 0, v[14:15]
	v_or_b32_sdwa v12, v16, v12 dst_sel:DWORD dst_unused:UNUSED_PAD src0_sel:DWORD src1_sel:WORD_1
	v_lshl_add_u64 v[14:15], v[14:15], 0, v[6:7]
	global_store_dwordx2 v[14:15], v[12:13], off offset:2048
	v_add_co_u32_e32 v12, vcc, s2, v10
	s_mov_b32 s2, 0x24000
	s_nop 0
	v_addc_co_u32_e32 v13, vcc, 0, v11, vcc
	s_waitcnt vmcnt(15)
	v_mov_b64_e32 v[12:13], v[64:65]
	v_mov_b64_e32 v[14:15], v[66:67]
	v_pk_mul_f32 v[14:15], v[148:149], v[14:15]
	v_pk_mul_f32 v[12:13], v[150:151], v[12:13]
	v_and_b32_sdwa v16, v14, v202 dst_sel:DWORD dst_unused:UNUSED_PAD src0_sel:WORD_1 src1_sel:DWORD
	v_and_b32_sdwa v17, v12, v202 dst_sel:DWORD dst_unused:UNUSED_PAD src0_sel:WORD_1 src1_sel:DWORD
	v_add3_u32 v14, v14, v16, s85
	v_and_b32_sdwa v16, v15, v202 dst_sel:DWORD dst_unused:UNUSED_PAD src0_sel:WORD_1 src1_sel:DWORD
	v_add3_u32 v12, v12, v17, s85
	v_and_b32_sdwa v17, v13, v202 dst_sel:DWORD dst_unused:UNUSED_PAD src0_sel:WORD_1 src1_sel:DWORD
	v_add3_u32 v15, v15, v16, s85
	v_add3_u32 v13, v13, v17, s85
	v_and_b32_e32 v15, 0xffff0000, v15
	v_and_b32_e32 v16, 0xffff0000, v13
	v_or_b32_sdwa v13, v15, v14 dst_sel:DWORD dst_unused:UNUSED_PAD src0_sel:DWORD src1_sel:WORD_1
	v_or_b32_e32 v14, 0xb000, v8
	v_mov_b32_e32 v15, v9
	v_lshl_add_u64 v[14:15], s[10:11], 0, v[14:15]
	v_or_b32_sdwa v12, v16, v12 dst_sel:DWORD dst_unused:UNUSED_PAD src0_sel:DWORD src1_sel:WORD_1
	v_lshl_add_u64 v[14:15], v[14:15], 0, v[6:7]
	global_store_dwordx2 v[14:15], v[12:13], off offset:2048
	v_add_co_u32_e32 v12, vcc, s2, v10
	s_mov_b32 s2, 0x27000
	s_nop 0
	v_addc_co_u32_e32 v13, vcc, 0, v11, vcc
	s_waitcnt vmcnt(15)
	v_mov_b64_e32 v[12:13], v[68:69]
	v_mov_b64_e32 v[14:15], v[70:71]
	v_pk_mul_f32 v[14:15], v[144:145], v[14:15]
	v_pk_mul_f32 v[12:13], v[146:147], v[12:13]
	v_and_b32_sdwa v16, v14, v202 dst_sel:DWORD dst_unused:UNUSED_PAD src0_sel:WORD_1 src1_sel:DWORD
	v_and_b32_sdwa v17, v12, v202 dst_sel:DWORD dst_unused:UNUSED_PAD src0_sel:WORD_1 src1_sel:DWORD
	v_add3_u32 v14, v14, v16, s85
	v_and_b32_sdwa v16, v15, v202 dst_sel:DWORD dst_unused:UNUSED_PAD src0_sel:WORD_1 src1_sel:DWORD
	v_add3_u32 v12, v12, v17, s85
	v_and_b32_sdwa v17, v13, v202 dst_sel:DWORD dst_unused:UNUSED_PAD src0_sel:WORD_1 src1_sel:DWORD
	v_add3_u32 v15, v15, v16, s85
	v_add3_u32 v13, v13, v17, s85
	v_and_b32_e32 v15, 0xffff0000, v15
	v_and_b32_e32 v16, 0xffff0000, v13
	v_or_b32_sdwa v13, v15, v14 dst_sel:DWORD dst_unused:UNUSED_PAD src0_sel:DWORD src1_sel:WORD_1
	v_or_b32_e32 v14, 0xc000, v8
	v_mov_b32_e32 v15, v9
	v_lshl_add_u64 v[14:15], s[10:11], 0, v[14:15]
	v_or_b32_sdwa v12, v16, v12 dst_sel:DWORD dst_unused:UNUSED_PAD src0_sel:DWORD src1_sel:WORD_1
	v_lshl_add_u64 v[14:15], v[14:15], 0, v[6:7]
	global_store_dwordx2 v[14:15], v[12:13], off offset:2048
	v_add_co_u32_e32 v12, vcc, s2, v10
	s_mov_b32 s2, 0x2a000
	s_nop 0
	v_addc_co_u32_e32 v13, vcc, 0, v11, vcc
	s_waitcnt vmcnt(15)
	v_mov_b64_e32 v[12:13], v[72:73]
	v_mov_b64_e32 v[14:15], v[74:75]
	v_pk_mul_f32 v[14:15], v[140:141], v[14:15]
	v_pk_mul_f32 v[12:13], v[142:143], v[12:13]
	v_and_b32_sdwa v16, v14, v202 dst_sel:DWORD dst_unused:UNUSED_PAD src0_sel:WORD_1 src1_sel:DWORD
	v_and_b32_sdwa v17, v12, v202 dst_sel:DWORD dst_unused:UNUSED_PAD src0_sel:WORD_1 src1_sel:DWORD
	v_add3_u32 v14, v14, v16, s85
	v_and_b32_sdwa v16, v15, v202 dst_sel:DWORD dst_unused:UNUSED_PAD src0_sel:WORD_1 src1_sel:DWORD
	v_add3_u32 v12, v12, v17, s85
	v_and_b32_sdwa v17, v13, v202 dst_sel:DWORD dst_unused:UNUSED_PAD src0_sel:WORD_1 src1_sel:DWORD
	v_add3_u32 v15, v15, v16, s85
	v_add3_u32 v13, v13, v17, s85
	v_and_b32_e32 v15, 0xffff0000, v15
	v_and_b32_e32 v16, 0xffff0000, v13
	v_or_b32_sdwa v13, v15, v14 dst_sel:DWORD dst_unused:UNUSED_PAD src0_sel:DWORD src1_sel:WORD_1
	v_or_b32_e32 v14, 0xd000, v8
	v_mov_b32_e32 v15, v9
	v_lshl_add_u64 v[14:15], s[10:11], 0, v[14:15]
	v_or_b32_sdwa v12, v16, v12 dst_sel:DWORD dst_unused:UNUSED_PAD src0_sel:DWORD src1_sel:WORD_1
	v_lshl_add_u64 v[14:15], v[14:15], 0, v[6:7]
	global_store_dwordx2 v[14:15], v[12:13], off offset:2048
	v_add_co_u32_e32 v12, vcc, s2, v10
	s_mov_b32 s2, 0x2d000
	s_nop 0
	v_addc_co_u32_e32 v13, vcc, 0, v11, vcc
	v_add_co_u32_e32 v10, vcc, s2, v10
	s_waitcnt vmcnt(15)
	v_mov_b64_e32 v[12:13], v[76:77]
	v_mov_b64_e32 v[14:15], v[78:79]
	v_pk_mul_f32 v[14:15], v[136:137], v[14:15]
	v_pk_mul_f32 v[12:13], v[138:139], v[12:13]
	v_and_b32_sdwa v16, v14, v202 dst_sel:DWORD dst_unused:UNUSED_PAD src0_sel:WORD_1 src1_sel:DWORD
	v_and_b32_sdwa v17, v12, v202 dst_sel:DWORD dst_unused:UNUSED_PAD src0_sel:WORD_1 src1_sel:DWORD
	v_add3_u32 v14, v14, v16, s85
	v_and_b32_sdwa v16, v15, v202 dst_sel:DWORD dst_unused:UNUSED_PAD src0_sel:WORD_1 src1_sel:DWORD
	v_add3_u32 v12, v12, v17, s85
	v_and_b32_sdwa v17, v13, v202 dst_sel:DWORD dst_unused:UNUSED_PAD src0_sel:WORD_1 src1_sel:DWORD
	v_add3_u32 v15, v15, v16, s85
	v_add3_u32 v13, v13, v17, s85
	v_and_b32_e32 v15, 0xffff0000, v15
	v_and_b32_e32 v16, 0xffff0000, v13
	v_or_b32_sdwa v13, v15, v14 dst_sel:DWORD dst_unused:UNUSED_PAD src0_sel:DWORD src1_sel:WORD_1
	v_or_b32_e32 v14, 0xe000, v8
	v_mov_b32_e32 v15, v9
	v_lshl_add_u64 v[14:15], s[10:11], 0, v[14:15]
	v_or_b32_sdwa v12, v16, v12 dst_sel:DWORD dst_unused:UNUSED_PAD src0_sel:DWORD src1_sel:WORD_1
	v_lshl_add_u64 v[14:15], v[14:15], 0, v[6:7]
	global_store_dwordx2 v[14:15], v[12:13], off offset:2048
	v_addc_co_u32_e32 v11, vcc, 0, v11, vcc
	v_or_b32_e32 v8, 0xf000, v8
	v_lshl_add_u64 v[8:9], s[10:11], 0, v[8:9]
	v_lshl_add_u64 v[6:7], v[8:9], 0, v[6:7]
	s_waitcnt vmcnt(15)
	v_mov_b64_e32 v[10:11], v[80:81]
	v_mov_b64_e32 v[12:13], v[82:83]
	v_pk_mul_f32 v[12:13], v[4:5], v[12:13]
	v_pk_mul_f32 v[10:11], v[2:3], v[10:11]
	v_and_b32_sdwa v14, v12, v202 dst_sel:DWORD dst_unused:UNUSED_PAD src0_sel:WORD_1 src1_sel:DWORD
	v_and_b32_sdwa v15, v10, v202 dst_sel:DWORD dst_unused:UNUSED_PAD src0_sel:WORD_1 src1_sel:DWORD
	v_add3_u32 v10, v10, v15, s85
	v_add3_u32 v12, v12, v14, s85
	v_and_b32_sdwa v14, v13, v202 dst_sel:DWORD dst_unused:UNUSED_PAD src0_sel:WORD_1 src1_sel:DWORD
	v_and_b32_sdwa v15, v11, v202 dst_sel:DWORD dst_unused:UNUSED_PAD src0_sel:WORD_1 src1_sel:DWORD
	v_add3_u32 v13, v13, v14, s85
	v_add3_u32 v11, v11, v15, s85
	v_and_b32_e32 v13, 0xffff0000, v13
	v_and_b32_e32 v14, 0xffff0000, v11
	v_or_b32_sdwa v11, v13, v12 dst_sel:DWORD dst_unused:UNUSED_PAD src0_sel:DWORD src1_sel:WORD_1
	v_or_b32_sdwa v10, v14, v10 dst_sel:DWORD dst_unused:UNUSED_PAD src0_sel:DWORD src1_sel:WORD_1
	global_store_dwordx2 v[6:7], v[10:11], off offset:2048
	s_and_saveexec_b64 s[22:23], s[8:9]
	s_cbranch_execz .LBB0_1670
	s_load_dwordx2 s[2:3], s[0:1], 0x1a8
	s_waitcnt lgkmcnt(0)
	s_add_u32 s4, s2, s26
	s_addc_u32 s5, s3, 0
	s_lshl_b64 s[2:3], s[20:21], 12
	s_add_u32 s2, s4, s2
	s_addc_u32 s3, s5, s3
	v_lshl_add_u64 v[6:7], s[2:3], 0, v[0:1]
	v_add_co_u32_e32 v6, vcc, 0x4a1a000, v6
	s_nop 1
	v_addc_co_u32_e32 v7, vcc, 0, v7, vcc
	global_store_dwordx4 v[6:7], v[2:5], off offset:1024
	s_branch .LBB0_1670
